# P5 epilogue staged residual loads, LDS-DMA with the nt hint like the loads they replace
# speedup vs baseline: 1.0021x; 1.0021x over previous
; __device__ __forceinline__ u32x4 pack8(const float (&v)[8]) { u32x4 w; w.x = cvtpk(v[0], v[1]); w.y = cvtpk(v[2], v[3]); w.z = cvtpk(v[4], v[5]); w.w = cvtpk(v[6], v[7]); return w; }
; #define LAS __attribute__((address_space(3)))
;     __device__ __forceinline__ void operator()(const pg8::f32x4 (&acc)[2][2][4][2], const pg8::Unit& u, int wr, int wc, int fr, int fq) const {
;         LAS char* xl = (LAS char*)xb + ((wr * 64 + fr) * 8 + wc) * 4; asm volatile("" : "+v"(xl));
;         const int b = u.pm >> 4; const float* mb = e.mod + (size_t)b * NMOD;
; #pragma unroll
;         for (int bj = 0; bj < 2; ++bj) {
;             const int c0 = u.pn * 256 + bj * 128 + wc * 32 + 8 * fq; float g1[8], gm[8];
; #pragma unroll
;             for (int h = 0; h < 2; ++h) { const f32x4 a = *(const f32x4*)(mb + 2 * DM + c0 + 4 * h), sc = *(const f32x4*)(mb + 4 * DM + c0 + 4 * h), ng = *(const f32x4*)(e.n2g + c0 + 4 * h);
; #pragma unroll
;                 for (int i = 0; i < 4; ++i) { g1[4 * h + i] = a[i]; gm[4 * h + i] = ng[i] * (1.0f + sc[i]); } }
; #pragma unroll
;             for (int ai = 0; ai < 2; ++ai) {
;                 f32x4 xa[4], xc[4];
; #pragma unroll
;                 for (int m = 0; m < 4; ++m) { const size_t off = (size_t)(u.pm * 256 + ai * 128 + wr * 64 + m * 16 + fr) * DM + c0; xa[m] = __builtin_nontemporal_load((const f32x4*)(e.x + off)); xc[m] = __builtin_nontemporal_load((const f32x4*)(e.x + off + 4)); }
; #pragma unroll
;                 for (int m = 0; m < 4; ++m) { ACC8(v, ai, bj, m); const size_t off = (size_t)(u.pm * 256 + ai * 128 + wr * 64 + m * 16 + fr) * DM + c0;
;                     float o[8], y[8], s = 0.f;
; #pragma unroll
;                     for (int i = 0; i < 8; ++i) { o[i] = (i < 4 ? xa[m][i & 3] : xc[m][i & 3]) + g1[i] * v[i]; s += o[i] * o[i]; y[i] = o[i] * gm[i]; }
;                     *(f32x4*)(e.out + off) = (f32x4){o[0], o[1], o[2], o[3]}; *(f32x4*)(e.out + off + 4) = (f32x4){o[4], o[5], o[6], o[7]};
;                     *(u32x4*)(e.Y2 + off) = pack8(y);
;                     s += __shfl_xor(s, 16); s += __shfl_xor(s, 32);
;                     if (fq == 0) *(LAS float*)(xl + ((ai * 128 + m * 16) * 8 + bj * 4) * 4) = s; }
.LBB9_668:
	s_cmp_lg_u64 s[6:7], 0
	s_cbranch_scc1 .Lp5o_668
	s_ashr_i32 s2, s30, 4
	s_mul_hi_i32 s3, s2, 0x6000
	s_mulk_i32 s2, 0x6000
	s_add_u32 s2, s48, s2
	s_addc_u32 s3, s49, s3
	s_add_u32 s34, s2, 0x2000
	s_addc_u32 s35, s3, 0
	s_add_u32 s36, s2, 0x4000
	v_lshl_or_b32 v176, s10, 8, v211
	s_addc_u32 s37, s3, 0
	s_lshl_b32 s11, s30, 8
	v_add_u32_e32 v198, s11, v209
	v_ashrrev_i32_e32 v177, 31, v176
	v_readlane_b32 s60, v251, 0
	v_lshlrev_b64 v[128:129], 2, v[176:177]
	v_readlane_b32 s61, v251, 1
	v_readlane_b32 s74, v251, 14
	v_readlane_b32 s75, v251, 15
	v_ashrrev_i32_e32 v199, 31, v198
	v_mov_b32_e32 v218, v212
	v_lshl_add_u64 v[130:131], s[34:35], 0, v[128:129]
	v_lshl_add_u64 v[132:133], s[36:37], 0, v[128:129]
	v_lshl_add_u64 v[178:179], s[74:75], 0, v[128:129]
	v_lshl_add_u64 v[200:201], s[60:61], 0, v[128:129]
	v_lshlrev_b64 v[128:129], 12, v[198:199]
	global_load_dwordx4 v[190:193], v[132:133], off offset:16
	global_load_dwordx4 v[194:197], v[132:133], off
	global_load_dwordx4 v[222:225], v[178:179], off offset:16
	global_load_dwordx4 v[226:229], v[178:179], off
	v_lshl_add_u64 v[182:183], v[200:201], 0, v[128:129]
	global_load_dwordx4 v[230:233], v[182:183], off nt
	global_load_dwordx4 v[132:135], v[130:131], off
	s_nop 0
	global_load_dwordx4 v[128:131], v[130:131], off offset:16
	s_nop 0
	global_load_dwordx4 v[234:237], v[182:183], off offset:16 nt
	v_or_b32_e32 v206, 16, v198
	v_or_b32_e32 v204, 32, v198
	v_or_b32_e32 v202, 48, v198
	v_ashrrev_i32_e32 v207, 31, v206
	v_ashrrev_i32_e32 v205, 31, v204
	v_ashrrev_i32_e32 v203, 31, v202
	v_lshlrev_b64 v[136:137], 12, v[206:207]
	v_lshlrev_b64 v[138:139], 12, v[204:205]
	v_lshlrev_b64 v[140:141], 12, v[202:203]
	v_lshl_add_u64 v[188:189], v[200:201], 0, v[136:137]
	v_lshl_add_u64 v[186:187], v[200:201], 0, v[138:139]
	v_lshl_add_u64 v[184:185], v[200:201], 0, v[140:141]
	global_load_dwordx4 v[152:155], v[188:189], off offset:16 nt
	global_load_dwordx4 v[156:159], v[188:189], off nt
	global_load_dwordx4 v[144:147], v[186:187], off offset:16 nt
	global_load_dwordx4 v[148:151], v[186:187], off nt
	global_load_dwordx4 v[136:139], v[184:185], off offset:16 nt
	global_load_dwordx4 v[140:143], v[184:185], off nt
	v_mbcnt_lo_u32_b32 v249, -1, 0
	v_mbcnt_hi_u32_b32 v249, -1, v249
	v_lshlrev_b32_e32 v249, 4, v249
	v_add_u32_e32 v249, s31, v249
	s_waitcnt vmcnt(14)
	s_mov_b32 s99, 0
	s_mov_b32 s98, 0x80000
	s_add_i32 m0, s31, 0x0
	v_lshl_add_u64 v[240:241], v[182:183], 0, s[98:99]
	global_load_lds_dwordx4 v[240:241], off nt
	s_mov_b32 s98, 0x80010
	s_add_i32 m0, s31, 0x4000
	v_lshl_add_u64 v[242:243], v[182:183], 0, s[98:99]
	global_load_lds_dwordx4 v[242:243], off nt
	s_mov_b32 s98, 0x80010
	s_add_i32 m0, s31, 0x8000
	v_lshl_add_u64 v[240:241], v[188:189], 0, s[98:99]
	global_load_lds_dwordx4 v[240:241], off nt
	s_mov_b32 s98, 0x80000
	s_add_i32 m0, s31, 0xc000
	v_lshl_add_u64 v[242:243], v[188:189], 0, s[98:99]
	global_load_lds_dwordx4 v[242:243], off nt
	s_mov_b32 s98, 0x80010
	s_add_i32 m0, s31, 0x2000
	v_lshl_add_u64 v[240:241], v[186:187], 0, s[98:99]
	global_load_lds_dwordx4 v[240:241], off nt
	s_mov_b32 s98, 0x80000
	s_add_i32 m0, s31, 0x6000
	v_lshl_add_u64 v[242:243], v[186:187], 0, s[98:99]
	global_load_lds_dwordx4 v[242:243], off nt
	s_mov_b32 s98, 0x80010
	s_add_i32 m0, s31, 0xa000
	v_lshl_add_u64 v[240:241], v[184:185], 0, s[98:99]
	global_load_lds_dwordx4 v[240:241], off nt
	s_mov_b32 s98, 0x80000
	s_add_i32 m0, s31, 0xe000
	v_lshl_add_u64 v[242:243], v[184:185], 0, s[98:99]
	global_load_lds_dwordx4 v[242:243], off nt
	v_and_b32_e32 v181, 64, v217
	v_xor_b32_e32 v180, 16, v217
	v_add_u32_e32 v181, 64, v181
	v_cmp_lt_i32_e32 vcc, v180, v181
	v_xor_b32_e32 v219, 32, v217
	v_readlane_b32 s62, v251, 2
	v_cndmask_b32_e32 v180, v217, v180, vcc
	v_lshlrev_b32_e32 v220, 2, v180
	v_cmp_lt_i32_e32 vcc, v219, v181
	v_readlane_b32 s63, v251, 3
	v_readlane_b32 s64, v251, 4
	v_cndmask_b32_e32 v181, v217, v219, vcc
	v_lshlrev_b32_e32 v219, 2, v181
	v_lshlrev_b64 v[180:181], 10, v[198:199]
	v_lshl_add_u64 v[238:239], v[180:181], 0, v[176:177]
	v_readlane_b32 s65, v251, 5
	v_readlane_b32 s66, v251, 6
	v_readlane_b32 s67, v251, 7
	v_readlane_b32 s68, v251, 8
	v_readlane_b32 s69, v251, 9
	v_readlane_b32 s70, v251, 10
	v_readlane_b32 s71, v251, 11
	v_readlane_b32 s72, v251, 12
	v_readlane_b32 s73, v251, 13
	s_waitcnt vmcnt(8)
	v_pk_add_f32 v[190:191], v[190:191], 1.0 op_sel_hi:[1,0]
	v_pk_add_f32 v[192:193], v[192:193], 1.0 op_sel_hi:[1,0]
	v_pk_mul_f32 v[190:191], v[222:223], v[190:191]
	v_pk_fma_f32 v[222:223], v[124:125], v[132:133], v[230:231]
	v_pk_mul_f32 v[192:193], v[224:225], v[192:193]
	v_pk_fma_f32 v[224:225], v[126:127], v[134:135], v[232:233]
	v_pk_mul_f32 v[126:127], v[222:223], v[222:223]
	v_pk_mul_f32 v[124:125], v[224:225], v[224:225]
	v_add_f32_e32 v126, v126, v127
	v_pk_fma_f32 v[120:121], v[120:121], v[128:129], v[234:235]
	v_add_f32_e32 v124, v124, v126
	v_pk_mul_f32 v[232:233], v[120:121], v[120:121]
	v_add_f32_e32 v124, v125, v124
	v_pk_fma_f32 v[122:123], v[122:123], v[130:131], v[236:237]
	v_add_f32_e32 v124, v232, v124
	v_pk_mul_f32 v[230:231], v[122:123], v[122:123]
	v_add_f32_e32 v124, v233, v124
	v_add_f32_e32 v124, v230, v124
	v_add_f32_e32 v124, v231, v124
	ds_bpermute_b32 v125, v220, v124
	v_lshl_add_u64 v[126:127], v[238:239], 2, s[88:89]
	v_pk_mul_f32 v[234:235], v[190:191], v[120:121]
	global_store_dwordx4 v[126:127], v[222:225], off
	global_store_dwordx4 v[126:127], v[120:123], off offset:16
	v_pk_add_f32 v[194:195], v[194:195], 1.0 op_sel_hi:[1,0]
	v_pk_add_f32 v[196:197], v[196:197], 1.0 op_sel_hi:[1,0]
	s_waitcnt lgkmcnt(0)
	v_add_f32_e32 v120, v124, v125
	ds_bpermute_b32 v121, v219, v120
	v_pk_mul_f32 v[194:195], v[226:227], v[194:195]
	v_pk_mul_f32 v[196:197], v[228:229], v[196:197]
	v_pk_mul_f32 v[226:227], v[194:195], v[222:223]
	v_pk_mul_f32 v[228:229], v[196:197], v[224:225]
	v_pk_mul_f32 v[236:237], v[192:193], v[122:123]
	v_cvt_pk_bf16_f32 v122, v226, v227
	v_cvt_pk_bf16_f32 v123, v228, v229
	v_cvt_pk_bf16_f32 v124, v234, v235
	v_cvt_pk_bf16_f32 v125, v236, v237
	v_lshl_add_u64 v[222:223], v[238:239], 1, s[16:17]
	global_store_dwordx4 v[222:223], v[122:125], off
	s_and_saveexec_b64 s[2:3], s[0:1]
	s_cbranch_execz .LBB9_670
	s_waitcnt lgkmcnt(0)
	v_add_f32_e32 v120, v120, v121
	ds_write_b32 v218, v120

; __device__ __forceinline__ u32x4 pack8(const float (&v)[8]) { u32x4 w; w.x = cvtpk(v[0], v[1]); w.y = cvtpk(v[2], v[3]); w.z = cvtpk(v[4], v[5]); w.w = cvtpk(v[6], v[7]); return w; }
; #define LAS __attribute__((address_space(3)))
;     __device__ __forceinline__ void operator()(const pg8::f32x4 (&acc)[2][2][4][2], const pg8::Unit& u, int wr, int wc, int fr, int fq) const {
;     ...
;             for (int ai = 0; ai < 2; ++ai) {
;                 f32x4 xa[4], xc[4];
; #pragma unroll
;                 for (int m = 0; m < 4; ++m) { const size_t off = (size_t)(u.pm * 256 + ai * 128 + wr * 64 + m * 16 + fr) * DM + c0; xa[m] = __builtin_nontemporal_load((const f32x4*)(e.x + off)); xc[m] = __builtin_nontemporal_load((const f32x4*)(e.x + off + 4)); }
; #pragma unroll
;                 for (int m = 0; m < 4; ++m) { ACC8(v, ai, bj, m); const size_t off = (size_t)(u.pm * 256 + ai * 128 + wr * 64 + m * 16 + fr) * DM + c0;
;                     float o[8], y[8], s = 0.f;
; #pragma unroll
;                     for (int i = 0; i < 8; ++i) { o[i] = (i < 4 ? xa[m][i & 3] : xc[m][i & 3]) + g1[i] * v[i]; s += o[i] * o[i]; y[i] = o[i] * gm[i]; }
;                     *(f32x4*)(e.out + off) = (f32x4){o[0], o[1], o[2], o[3]}; *(f32x4*)(e.out + off + 4) = (f32x4){o[4], o[5], o[6], o[7]};
;                     *(u32x4*)(e.Y2 + off) = pack8(y);
;                     s += __shfl_xor(s, 16); s += __shfl_xor(s, 32);
;                     if (fq == 0) *(LAS float*)(xl + ((ai * 128 + m * 16) * 8 + bj * 4) * 4) = s; }
.LBB9_684:
	s_or_b64 exec, exec, s[2:3]
	v_or_b32_e32 v98, 0x80, v176
	v_ashrrev_i32_e32 v99, 31, v98
	s_waitcnt lgkmcnt(0)
	v_lshlrev_b64 v[64:65], 2, v[98:99]
	v_lshl_add_u64 v[66:67], s[36:37], 0, v[64:65]
	global_load_dwordx4 v[100:103], v[66:67], off
	global_load_dwordx4 v[108:111], v[66:67], off offset:16
	v_lshl_add_u64 v[68:69], s[34:35], 0, v[64:65]
	global_load_dwordx4 v[64:67], v[68:69], off
	global_load_dwordx4 v[116:119], v[182:183], off offset:512 nt
	global_load_dwordx4 v[128:131], v[182:183], off offset:528 nt
	s_nop 0
	global_load_dwordx4 v[68:71], v[68:69], off offset:16
	s_nop 0
	global_load_dwordx4 v[132:135], v[178:179], off offset:512
	global_load_dwordx4 v[156:159], v[178:179], off offset:528
	global_load_dwordx4 v[88:91], v[188:189], off offset:528 nt
	global_load_dwordx4 v[92:95], v[188:189], off offset:512 nt
	global_load_dwordx4 v[80:83], v[186:187], off offset:528 nt
	global_load_dwordx4 v[84:87], v[186:187], off offset:512 nt
	global_load_dwordx4 v[72:75], v[184:185], off offset:528 nt
	global_load_dwordx4 v[76:79], v[184:185], off offset:512 nt
	s_mov_b32 s99, 0
	s_mov_b32 s98, 0x80200
	s_add_i32 m0, s31, 0x0
	v_lshl_add_u64 v[240:241], v[182:183], 0, s[98:99]
	global_load_lds_dwordx4 v[240:241], off nt
	s_mov_b32 s98, 0x80210
	s_add_i32 m0, s31, 0x4000
	v_lshl_add_u64 v[242:243], v[182:183], 0, s[98:99]
	global_load_lds_dwordx4 v[242:243], off nt
	s_mov_b32 s98, 0x80210
	s_add_i32 m0, s31, 0x8000
	v_lshl_add_u64 v[240:241], v[188:189], 0, s[98:99]
	global_load_lds_dwordx4 v[240:241], off nt
	s_mov_b32 s98, 0x80200
	s_add_i32 m0, s31, 0xc000
	v_lshl_add_u64 v[242:243], v[188:189], 0, s[98:99]
	global_load_lds_dwordx4 v[242:243], off nt
	s_mov_b32 s98, 0x80210
	s_add_i32 m0, s31, 0x2000
	v_lshl_add_u64 v[240:241], v[186:187], 0, s[98:99]
	global_load_lds_dwordx4 v[240:241], off nt
	s_mov_b32 s98, 0x80200
	s_add_i32 m0, s31, 0x6000
	v_lshl_add_u64 v[242:243], v[186:187], 0, s[98:99]
	global_load_lds_dwordx4 v[242:243], off nt
	s_mov_b32 s98, 0x80210
	s_add_i32 m0, s31, 0xa000
	v_lshl_add_u64 v[240:241], v[184:185], 0, s[98:99]
	global_load_lds_dwordx4 v[240:241], off nt
	s_mov_b32 s98, 0x80200
	s_add_i32 m0, s31, 0xe000
	v_lshl_add_u64 v[242:243], v[184:185], 0, s[98:99]
	global_load_lds_dwordx4 v[242:243], off nt
	s_waitcnt vmcnt(21)
	v_pk_add_f32 v[176:177], v[100:101], 1.0 op_sel_hi:[1,0]
	s_waitcnt vmcnt(18)
	v_pk_fma_f32 v[100:101], v[60:61], v[64:65], v[116:117]
	v_pk_add_f32 v[178:179], v[102:103], 1.0 op_sel_hi:[1,0]
	v_pk_fma_f32 v[102:103], v[62:63], v[66:67], v[118:119]
	v_pk_mul_f32 v[118:119], v[100:101], v[100:101]
	v_pk_mul_f32 v[116:117], v[102:103], v[102:103]
	v_add_f32_e32 v118, v118, v119
	v_pk_add_f32 v[182:183], v[108:109], 1.0 op_sel_hi:[1,0]
	s_waitcnt vmcnt(16)
	v_pk_fma_f32 v[108:109], v[56:57], v[68:69], v[128:129]
	v_add_f32_e32 v116, v116, v118
	v_pk_add_f32 v[184:185], v[110:111], 1.0 op_sel_hi:[1,0]
	v_pk_fma_f32 v[110:111], v[58:59], v[70:71], v[130:131]
	v_pk_mul_f32 v[130:131], v[108:109], v[108:109]
	v_add_f32_e32 v116, v117, v116
	v_add_f32_e32 v116, v130, v116
	v_pk_mul_f32 v[128:129], v[110:111], v[110:111]
	v_add_f32_e32 v116, v131, v116
	v_add_f32_e32 v116, v128, v116
	v_add_f32_e32 v118, v129, v116
	ds_bpermute_b32 v119, v220, v118
	s_waitcnt vmcnt(15)
	v_pk_mul_f32 v[60:61], v[132:133], v[176:177]
	global_store_dwordx4 v[126:127], v[100:103], off offset:512
	global_store_dwordx4 v[126:127], v[108:111], off offset:528
	v_pk_mul_f32 v[132:133], v[60:61], v[100:101]
	v_pk_mul_f32 v[62:63], v[134:135], v[178:179]
	s_waitcnt lgkmcnt(0)
	v_add_f32_e32 v100, v118, v119
	ds_bpermute_b32 v101, v219, v100
	s_waitcnt vmcnt(16)
	v_pk_mul_f32 v[56:57], v[156:157], v[182:183]
	v_pk_mul_f32 v[58:59], v[158:159], v[184:185]
	v_pk_mul_f32 v[134:135], v[62:63], v[102:103]
	v_pk_mul_f32 v[156:157], v[56:57], v[108:109]
	v_pk_mul_f32 v[158:159], v[58:59], v[110:111]
	v_lshl_add_u64 v[116:117], v[180:181], 0, v[98:99]
	v_cvt_pk_bf16_f32 v108, v132, v133
	v_cvt_pk_bf16_f32 v109, v134, v135
	v_cvt_pk_bf16_f32 v110, v156, v157
	v_cvt_pk_bf16_f32 v111, v158, v159
	v_lshl_add_u64 v[102:103], v[116:117], 1, s[16:17]
	global_store_dwordx4 v[102:103], v[108:111], off
	s_and_saveexec_b64 s[2:3], s[0:1]
	s_cbranch_execz .LBB9_686
	s_waitcnt lgkmcnt(0)
	v_add_f32_e32 v100, v100, v101
	ds_write_b32 v218, v100 offset:16
